# MLA attention loop hand-pipelined too (speculative exps for two key steps, third P buffer, selected per-lane K pointers, 5-slot ring)
# speedup vs baseline: 1.0210x; 1.0145x over previous
; #define LAS __attribute__((address_space(3)))
; template <int D1, int D2, int DV>
; DI void attn_core(f32x16 (&o)[DV / 32], float& l_out, LAS unsigned char* lds, const bf16_t* q1, const bf16_t* q2,
;                   const bf16_t* k1, long ldk1, const bf16_t* k2, long ldk2, const bf16_t* vt, long ldv, int ntiles) {
;     ...
;     const int pr = (r & ~12) | ((r & 4) << 1) | ((r & 8) >> 1);
;     float mrun = 0.f, lrun = 0.f;
;     f32x16 negm;
; #pragma unroll
;     for (int i = 0; i < 16; ++i) negm[i] = 0.f;
; #pragma unroll
;     for (int b = 0; b < DV / 32; ++b)
; #pragma unroll
;         for (int i = 0; i < 16; ++i) o[b][i] = 0.f;
;     gload(0); sstore(0); if (ntiles > 1) { gload(1); sstore(1); } __syncthreads();
;     for (int t = 0; t < ntiles; ++t) {
;         if (t + 2 < ntiles) gload(t + 2);
;         const LAS unsigned char* kb = lds + (t & 3) * BUF; const LAS unsigned char* vb = kb + KT;
;         f32x16 p[2];
;         {
;             bf16x8 kf[2][DQK / 16];
; #pragma unroll
;             for (int hf = 0; hf < 2; ++hf)
; #pragma unroll
;                 for (int d0 = 0; d0 < DQK / 16; ++d0) kf[hf][d0] = *(const LAS bf16x8*)(kb + (32 * hf + pr) * KROW + (16 * d0 + 8 * h) * 2);
;             __builtin_amdgcn_sched_barrier(0);
;             __builtin_amdgcn_s_setprio(2);
; #pragma unroll
;             for (int d0 = 0; d0 < DQK / 16; ++d0)
; #pragma unroll
;                 for (int hf = 0; hf < 2; ++hf) p[hf] = MFMA32(kf[hf][d0], qf[d0], d0 == 0 ? negm : p[hf]);
;             __builtin_amdgcn_sched_barrier(0);
;         }
;         constexpr int NBLK = DV / 32;
;         bf16x8 vk[2][NBLK];
;     ...
;         LDVK(0, 0);
;         __builtin_amdgcn_sched_barrier(0);
;         float ta = fmaxf(fmaxf(p[0][0], p[0][1]), p[1][0]), tb = fmaxf(fmaxf(p[0][2], p[0][3]), p[1][1]);
;         ta = fmaxf(fmaxf(ta, p[1][2]), p[1][3]);
; #pragma unroll
;         for (int i = 4; i < 16; i += 4) { ta = fmaxf(fmaxf(ta, p[0][i]), p[0][i + 1]); tb = fmaxf(fmaxf(tb, p[0][i + 2]), p[0][i + 3]); ta = fmaxf(fmaxf(ta, p[1][i]), p[1][i + 1]); tb = fmaxf(fmaxf(tb, p[1][i + 2]), p[1][i + 3]); }
;         float tm = fmaxf(ta, tb);
;         if (__any(t == 0 || tm > 8.0f)) {
;             tm = fmaxf(tm, __shfl_xor(tm, 32));
;             const float dl = (t == 0 || tm > 0.f) ? tm : 0.f; mrun += dl;
;             const float alpha = __builtin_amdgcn_exp2f(-dl); lrun *= alpha;
; #pragma unroll
.LBB0_319:
	s_or_b64 exec, exec, s[0:1]
	v_mul_u32_u24_e32 v146, 0xd0, v1
	v_add_f32_e32 v1, 0, v64
	v_add_f32_e32 v1, v65, v1
	v_add_f32_e32 v1, v66, v1
	v_add_f32_e32 v1, v67, v1
	v_add_f32_e32 v1, v68, v1
	v_add_f32_e32 v1, v69, v1
	v_add_f32_e32 v1, v70, v1
	v_add_f32_e32 v1, v71, v1
	v_add_f32_e32 v1, v72, v1
	v_add_f32_e32 v1, v73, v1
	v_add_f32_e32 v1, v74, v1
	v_add_f32_e32 v1, v75, v1
	v_add_f32_e32 v1, v76, v1
	v_add_f32_e32 v1, v77, v1
	v_add_f32_e32 v1, v3, v1
	v_add_f32_e32 v1, v4, v1
	v_add_f32_e32 v1, v5, v1
	v_add_f32_e32 v1, v6, v1
	v_add_f32_e32 v1, v7, v1
	v_add_f32_e32 v1, v8, v1
	v_add_f32_e32 v1, v9, v1
	v_add_f32_e32 v1, v10, v1
	v_add_f32_e32 v1, v11, v1
	v_add_f32_e32 v1, v12, v1
	v_add_f32_e32 v1, v13, v1
	v_add_f32_e32 v1, v14, v1
	v_add_f32_e32 v1, v15, v1
	v_add_f32_e32 v1, v48, v1
	v_add_f32_e32 v1, v49, v1
	v_add_f32_e32 v1, v50, v1
	v_add_f32_e32 v1, v51, v1
	s_cmp_eq_u32 s5, 0
	v_add_f32_e32 v1, v52, v1
	s_cselect_b32 s5, 4, 0x84
	v_ashrrev_i32_e32 v131, 31, v130
	s_add_u32 s0, s30, s28
	v_add_f32_e32 v147, v2, v1
	v_lshlrev_b64 v[2:3], 10, v[130:131]
	s_addc_u32 s1, 0, s29
	v_lshl_add_u64 v[2:3], v[2:3], 0, s[0:1]
	v_lshl_add_u64 v[2:3], v[128:129], 1, v[2:3]
	s_mov_b64 s[8:9], 0x19f30000
	v_lshl_add_u64 v[128:129], v[2:3], 0, s[8:9]
	v_lshlrev_b64 v[2:3], 6, v[130:131]
	v_lshl_add_u64 v[2:3], v[2:3], 0, s[58:59]
	s_waitcnt vmcnt(0)
	ds_write_b128 v123, v[112:115] offset:58368
	v_lshl_add_u64 v[2:3], v[156:157], 1, v[2:3]
	s_mov_b64 s[12:13], 0x1c002f80
	v_ashrrev_i32_e32 v123, 31, v122
	v_lshl_add_u64 v[130:131], v[2:3], 0, s[12:13]
	v_lshlrev_b64 v[2:3], 10, v[122:123]
	v_lshl_add_u64 v[2:3], v[2:3], 0, s[0:1]
	v_lshl_add_u64 v[2:3], v[132:133], 1, v[2:3]
	v_lshl_add_u64 v[132:133], v[2:3], 0, s[8:9]
	v_lshlrev_b64 v[2:3], 6, v[122:123]
	v_lshl_add_u64 v[2:3], v[2:3], 0, s[58:59]
	s_add_u32 s0, s7, 0x1c210180
	v_lshl_add_u64 v[2:3], v[134:135], 1, v[2:3]
	s_addc_u32 s1, 0, 0
	v_and_b32_e32 v1, 7, v136
	v_lshl_add_u64 v[134:135], v[2:3], 0, s[12:13]
	v_lshl_add_u64 v[2:3], s[0:1], 0, v[120:121]
	v_lshlrev_b32_e32 v156, 4, v1
	v_lshl_add_u64 v[2:3], v[2:3], 0, v[156:157]
	s_mov_b32 s6, 1
	v_lshl_add_u64 v[136:137], s[18:19], 1, v[2:3]
	v_mov_b32_e32 v1, v0
	v_mov_b32_e32 v2, v0
	v_mov_b32_e32 v3, v0
	v_mov_b32_e32 v4, v0
	v_mov_b32_e32 v5, v0
	v_mov_b32_e32 v6, v0
	v_mov_b32_e32 v7, v0
	v_mov_b32_e32 v8, v0
	v_mov_b32_e32 v9, v0
	v_mov_b32_e32 v10, v0
	v_mov_b32_e32 v11, v0
	v_mov_b32_e32 v12, v0
	v_mov_b32_e32 v13, v0
	v_mov_b32_e32 v14, v0
	v_mov_b32_e32 v15, v0
	v_lshl_add_u64 v[216:217], s[16:17], 0, v[128:129]
	v_lshl_add_u64 v[218:219], s[16:17], 0, v[130:131]
	v_cndmask_b32_e64 v128, v218, v216, s[44:45]
	v_cndmask_b32_e64 v129, v219, v217, s[44:45]
	v_mov_b32_e32 v220, 0x1000
	v_mov_b32_e32 v221, 0x10000
	v_lshl_add_u64 v[216:217], s[16:17], 0, v[132:133]
	v_lshl_add_u64 v[218:219], s[16:17], 0, v[134:135]
	v_cndmask_b32_e64 v132, v218, v216, s[46:47]
	v_cndmask_b32_e64 v133, v219, v217, s[46:47]
	v_cndmask_b32_e64 v130, v220, v221, s[44:45]
	v_mov_b32_e32 v131, 0
	v_cndmask_b32_e64 v134, v220, v221, s[46:47]
	v_mov_b32_e32 v135, 0
	v_cndmask_b32_e64 v132, v128, v132, s[42:43]
	v_cndmask_b32_e64 v133, v129, v133, s[42:43]
	v_cndmask_b32_e64 v134, v130, v134, s[42:43]
	v_and_b32_e32 v220, 63, v168
	v_mul_u32_u24_e32 v220, 0xd0, v220
	v_add_u32_e32 v220, 0xc0, v220
	v_add_u32_e32 v221, v139, v140
	v_cndmask_b32_e64 v236, v220, v221, s[42:43]
	v_lshl_add_u64 v[136:137], s[16:17], 0, v[136:137]
	v_and_b32_e32 v220, 64, v186
	v_xor_b32_e32 v221, 32, v186
	v_add_u32_e32 v220, 64, v220
	v_cmp_lt_i32_e32 vcc, v221, v220
	s_nop 1
	v_cndmask_b32_e32 v221, v186, v221, vcc
	v_lshlrev_b32_e32 v237, 2, v221
	global_load_dwordx4 v[104:107], v[128:129], off
	global_load_dwordx4 v[108:111], v[132:133], off
	global_load_dwordx4 v[112:115], v[136:137], off
	v_lshl_add_u64 v[128:129], v[128:129], 0, v[130:131]
	v_lshl_add_u64 v[132:133], v[132:133], 0, v[134:135]
	s_mov_b64 s[0:1], 0x80
	v_lshl_add_u64 v[136:137], v[136:137], 0, s[0:1]
	s_waitcnt lgkmcnt(0)
	s_movk_i32 s8, 0x5800
	v_add3_u32 v233, s8, v146, v141
	ds_read_b128 v[116:119], v233 offset:0
	ds_read_b128 v[120:123], v233 offset:32
	ds_read_b128 v[148:151], v233 offset:64
	ds_read_b128 v[152:155], v233 offset:96
	v_add3_u32 v232, s8, v143, v141
	s_waitcnt lgkmcnt(3)
	v_mfma_f32_32x32x16_bf16 v[64:79], v[116:119], v[80:83], v[0:15]
	ds_read_b128 v[116:119], v233 offset:128
	s_waitcnt lgkmcnt(3)
	v_mfma_f32_32x32x16_bf16 v[64:79], v[120:123], v[84:87], v[64:79]
	ds_read_b128 v[120:123], v233 offset:160
	s_waitcnt lgkmcnt(3)
	v_mfma_f32_32x32x16_bf16 v[64:79], v[148:151], v[88:91], v[64:79]
	ds_read_b128 v[148:151], v233 offset:6656
	s_waitcnt lgkmcnt(3)
	v_mfma_f32_32x32x16_bf16 v[64:79], v[152:155], v[92:95], v[64:79]
	ds_read_b128 v[152:155], v233 offset:6688
	s_waitcnt lgkmcnt(3)
	v_mfma_f32_32x32x16_bf16 v[64:79], v[116:119], v[96:99], v[64:79]
	ds_read_b128 v[116:119], v233 offset:6720
	s_waitcnt lgkmcnt(3)
	v_mfma_f32_32x32x16_bf16 v[64:79], v[120:123], v[100:103], v[64:79]
	ds_read_b128 v[120:123], v233 offset:6752
	s_waitcnt lgkmcnt(3)
	v_mfma_f32_32x32x16_bf16 v[48:63], v[148:151], v[80:83], v[0:15]
	ds_read_b128 v[148:151], v233 offset:6784
	s_waitcnt lgkmcnt(3)
	v_mfma_f32_32x32x16_bf16 v[48:63], v[152:155], v[84:87], v[48:63]
	ds_read_b128 v[152:155], v233 offset:6816
	s_waitcnt lgkmcnt(3)
	v_mfma_f32_32x32x16_bf16 v[48:63], v[116:119], v[88:91], v[48:63]
	s_waitcnt lgkmcnt(2)
	v_mfma_f32_32x32x16_bf16 v[48:63], v[120:123], v[92:95], v[48:63]
	s_waitcnt lgkmcnt(1)
	v_mfma_f32_32x32x16_bf16 v[48:63], v[148:151], v[96:99], v[48:63]
	s_waitcnt lgkmcnt(0)
	v_mfma_f32_32x32x16_bf16 v[48:63], v[152:155], v[100:103], v[48:63]
	ds_read_b128 v[158:161], v232 offset:13312
	ds_read_b128 v[162:165], v232 offset:17920
	ds_read_b128 v[190:193], v232 offset:13344
	ds_read_b128 v[194:197], v232 offset:17952
	s_nop 15
	v_exp_f32_e32 v216, v64
	v_exp_f32_e32 v217, v65
	v_exp_f32_e32 v218, v66
	v_exp_f32_e32 v219, v67
	v_exp_f32_e32 v220, v68
	v_exp_f32_e32 v221, v69
	v_exp_f32_e32 v222, v70
	v_exp_f32_e32 v223, v71
	v_exp_f32_e32 v224, v72
	v_exp_f32_e32 v225, v73
	v_exp_f32_e32 v226, v74
	v_exp_f32_e32 v227, v75
	v_exp_f32_e32 v228, v76
	v_exp_f32_e32 v229, v77
	v_exp_f32_e32 v230, v78
	v_exp_f32_e32 v231, v79
	s_nop 0
	v_cvt_pk_bf16_f32 v198, v216, v217
	v_cvt_pk_bf16_f32 v199, v218, v219
	v_cvt_pk_bf16_f32 v200, v220, v221
	v_cvt_pk_bf16_f32 v201, v222, v223
	v_cvt_pk_bf16_f32 v208, v224, v225
	v_cvt_pk_bf16_f32 v209, v226, v227
	v_cvt_pk_bf16_f32 v210, v228, v229
	v_cvt_pk_bf16_f32 v211, v230, v231
	s_mov_b32 s18, 0x10800
	s_waitcnt vmcnt(0)
	v_add3_u32 v233, s18, v144, v145
	ds_write_b128 v233, v[104:107] offset:0
	v_add_u32_e32 v233, s18, v236
	ds_write_b128 v233, v[108:111] offset:0
	v_add3_u32 v233, s18, v127, v126
	ds_write_b128 v233, v[112:115] offset:13312
	s_mov_b32 s7, 0x5800
	s_mov_b32 s8, 0xb000
	s_mov_b32 s18, 0x16000
	s_waitcnt lgkmcnt(0)
; template <int D1, int D2, int DV>
; DI void attn_core(f32x16 (&o)[DV / 32], float& l_out, LAS unsigned char* lds, const bf16_t* q1, const bf16_t* q2,
;                   const bf16_t* k1, long ldk1, const bf16_t* k2, long ldk2, const bf16_t* vt, long ldv, int ntiles) {
;     ...
;     for (int t = 0; t < ntiles; ++t) {
;         if (t + 2 < ntiles) gload(t + 2);
;         const LAS unsigned char* kb = lds + (t & 3) * BUF; const LAS unsigned char* vb = kb + KT;
;         f32x16 p[2];
;         {
;             bf16x8 kf[2][DQK / 16];
; #pragma unroll
;             for (int hf = 0; hf < 2; ++hf)
; #pragma unroll
;                 for (int d0 = 0; d0 < DQK / 16; ++d0) kf[hf][d0] = *(const LAS bf16x8*)(kb + (32 * hf + pr) * KROW + (16 * d0 + 8 * h) * 2);
;             __builtin_amdgcn_sched_barrier(0);
;             __builtin_amdgcn_s_setprio(2);
; #pragma unroll
;             for (int d0 = 0; d0 < DQK / 16; ++d0)
; #pragma unroll
;                 for (int hf = 0; hf < 2; ++hf) p[hf] = MFMA32(kf[hf][d0], qf[d0], d0 == 0 ? negm : p[hf]);
;             __builtin_amdgcn_sched_barrier(0);
;         }
;         constexpr int NBLK = DV / 32;
;         bf16x8 vk[2][NBLK];
;     ...
;         LDVK(0, 0);
;         __builtin_amdgcn_sched_barrier(0);
;         float ta = fmaxf(fmaxf(p[0][0], p[0][1]), p[1][0]), tb = fmaxf(fmaxf(p[0][2], p[0][3]), p[1][1]);
;         ta = fmaxf(fmaxf(ta, p[1][2]), p[1][3]);
; #pragma unroll
;         for (int i = 4; i < 16; i += 4) { ta = fmaxf(fmaxf(ta, p[0][i]), p[0][i + 1]); tb = fmaxf(fmaxf(tb, p[0][i + 2]), p[0][i + 3]); ta = fmaxf(fmaxf(ta, p[1][i]), p[1][i + 1]); tb = fmaxf(fmaxf(tb, p[1][i + 2]), p[1][i + 3]); }
;         float tm = fmaxf(ta, tb);
;         if (__any(t == 0 || tm > 8.0f)) {
;             tm = fmaxf(tm, __shfl_xor(tm, 32));
;             const float dl = (t == 0 || tm > 0.f) ? tm : 0.f; mrun += dl;
;             const float alpha = __builtin_amdgcn_exp2f(-dl); lrun *= alpha;
; #pragma unroll
;             for (int i = 0; i < 16; ++i) { p[0][i] -= dl; p[1][i] -= dl; negm[i] = -mrun; }
; #pragma unroll
;             for (int b = 0; b < DV / 32; ++b)
; #pragma unroll
;                 for (int i = 0; i < 16; ++i) o[b][i] *= alpha;
;         }
;         bf16x8 pf[4]; float rs = 0.f; u32x4 wq;
;     ...
;         EXPPART(0, 0); EXPPART(0, 1); EXPPART(0, 2); EXPPART(0, 3); pf[0] = __builtin_bit_cast(bf16x8, wq);
.Lml_top:
	v_add3_u32 v232, s7, v143, v141
	s_add_i32 s19, s6, 3
	s_cmp_lt_u32 s19, s5
	s_cbranch_scc0 .Lml_nog
	global_load_dwordx4 v[104:107], v[128:129], off
	global_load_dwordx4 v[108:111], v[132:133], off
	global_load_dwordx4 v[112:115], v[136:137], off
	v_lshl_add_u64 v[128:129], v[128:129], 0, v[130:131]
	v_lshl_add_u64 v[132:133], v[132:133], 0, v[134:135]
	s_mov_b64 s[0:1], 0x80
	v_lshl_add_u64 v[136:137], v[136:137], 0, s[0:1]
.Lml_nog:
	v_mfma_f32_32x32x16_bf16 v[32:47], v[158:161], v[198:201], v[32:47]
	v_exp_f32_e32 v48, v48
	ds_read_b128 v[158:161], v232 offset:13376
	v_add_f32_e32 v234, v216, v217
	v_exp_f32_e32 v56, v56
	v_add_f32_e32 v235, v218, v219
	v_mfma_f32_32x32x16_bf16 v[16:31], v[162:165], v[198:201], v[16:31]
	v_exp_f32_e32 v49, v49
	ds_read_b128 v[162:165], v232 offset:17984
	v_add_f32_e32 v234, v220, v234
	v_exp_f32_e32 v57, v57
	v_add_f32_e32 v235, v221, v235
	v_cvt_pk_bf16_f32 v198, v48, v49
	s_bitcmp1_b32 s6, 0
	s_cbranch_scc0 .Lml_nobar
	s_barrier
.Lml_nobar:
	v_add3_u32 v233, s8, v146, v141
	ds_read_b128 v[116:119], v233 offset:0
	ds_read_b128 v[120:123], v233 offset:32
	ds_read_b128 v[148:151], v233 offset:64
	ds_read_b128 v[152:155], v233 offset:96
	s_waitcnt lgkmcnt(3)
	v_mfma_f32_32x32x16_bf16 v[64:79], v[116:119], v[80:83], v[0:15]
	v_exp_f32_e32 v50, v50
	ds_read_b128 v[116:119], v233 offset:128
	v_add_f32_e32 v234, v222, v234
	v_exp_f32_e32 v58, v58
	v_add_f32_e32 v235, v223, v235
	s_waitcnt lgkmcnt(3)
	v_mfma_f32_32x32x16_bf16 v[64:79], v[120:123], v[84:87], v[64:79]
	v_exp_f32_e32 v51, v51
	ds_read_b128 v[120:123], v233 offset:160
	v_add_f32_e32 v234, v224, v234
	v_exp_f32_e32 v59, v59
	v_add_f32_e32 v235, v225, v235
	v_cvt_pk_bf16_f32 v199, v50, v51
	s_waitcnt lgkmcnt(3)
	v_mfma_f32_32x32x16_bf16 v[64:79], v[148:151], v[88:91], v[64:79]
	v_exp_f32_e32 v52, v52
	ds_read_b128 v[148:151], v233 offset:6656
	v_add_f32_e32 v234, v226, v234
	v_exp_f32_e32 v60, v60
	v_add_f32_e32 v235, v227, v235
	s_waitcnt lgkmcnt(3)
	v_mfma_f32_32x32x16_bf16 v[64:79], v[152:155], v[92:95], v[64:79]
	v_exp_f32_e32 v53, v53
	ds_read_b128 v[152:155], v233 offset:6688
	v_add_f32_e32 v234, v228, v234
	v_exp_f32_e32 v61, v61
	v_add_f32_e32 v235, v229, v235
	v_cvt_pk_bf16_f32 v200, v52, v53
	s_waitcnt lgkmcnt(3)
	v_mfma_f32_32x32x16_bf16 v[64:79], v[116:119], v[96:99], v[64:79]
	v_exp_f32_e32 v54, v54
	ds_read_b128 v[116:119], v233 offset:6720
	v_add_f32_e32 v234, v230, v234
	v_exp_f32_e32 v62, v62
	v_add_f32_e32 v235, v231, v235
	s_waitcnt lgkmcnt(3)
	v_mfma_f32_32x32x16_bf16 v[64:79], v[120:123], v[100:103], v[64:79]
	v_exp_f32_e32 v55, v55
	ds_read_b128 v[120:123], v233 offset:6752
	s_nop 0
	v_exp_f32_e32 v63, v63
	v_cvt_pk_bf16_f32 v201, v54, v55
	v_mfma_f32_32x32x16_bf16 v[32:47], v[190:193], v[208:211], v[32:47]
	v_add_f32_e32 v234, v48, v234
	ds_read_b128 v[190:193], v232 offset:13408
	v_add_f32_e32 v235, v56, v235
	v_add_f32_e32 v234, v49, v234
	v_add_f32_e32 v235, v57, v235
	v_add_f32_e32 v234, v50, v234
	v_add_f32_e32 v234, v51, v234
	v_mfma_f32_32x32x16_bf16 v[16:31], v[194:197], v[208:211], v[16:31]
	v_add_f32_e32 v234, v52, v234
	ds_read_b128 v[194:197], v232 offset:18016
	v_add_f32_e32 v235, v58, v235
	v_add_f32_e32 v234, v53, v234
	v_add_f32_e32 v235, v59, v235
	v_add_f32_e32 v234, v54, v234
	v_add_f32_e32 v234, v55, v234
	v_add3_u32 v232, s8, v143, v141
	v_mfma_f32_32x32x16_bf16 v[32:47], v[158:161], v[198:201], v[32:47]
	v_cvt_pk_bf16_f32 v212, v56, v57
	ds_read_b128 v[158:161], v232 offset:13312
	v_add_f32_e32 v235, v60, v235
	v_cvt_pk_bf16_f32 v213, v58, v59
	v_add_f32_e32 v234, v61, v234
	v_exp_f32_e32 v216, v64
	v_mfma_f32_32x32x16_bf16 v[16:31], v[162:165], v[198:201], v[16:31]
	v_cvt_pk_bf16_f32 v214, v60, v61
	ds_read_b128 v[162:165], v232 offset:17920
	v_add_f32_e32 v235, v62, v235
	v_cvt_pk_bf16_f32 v215, v62, v63
	v_add_f32_e32 v234, v63, v234
	v_exp_f32_e32 v217, v65
	s_waitcnt lgkmcnt(7)
	v_mfma_f32_32x32x16_bf16 v[48:63], v[148:151], v[80:83], v[0:15]
	v_add_f32_e32 v234, v235, v234
	ds_read_b128 v[148:151], v233 offset:6784
	v_add_f32_e32 v147, v234, v147
	v_exp_f32_e32 v218, v66
	v_exp_f32_e32 v219, v67
	s_waitcnt lgkmcnt(7)
	v_mfma_f32_32x32x16_bf16 v[48:63], v[152:155], v[84:87], v[48:63]
	v_exp_f32_e32 v220, v68
	ds_read_b128 v[152:155], v233 offset:6816
	v_exp_f32_e32 v221, v69
	v_cvt_pk_bf16_f32 v198, v216, v217
	s_waitcnt lgkmcnt(7)
	v_mfma_f32_32x32x16_bf16 v[48:63], v[116:119], v[88:91], v[48:63]
	v_exp_f32_e32 v222, v70
	v_exp_f32_e32 v223, v71
	v_cvt_pk_bf16_f32 v199, v218, v219
	s_waitcnt vmcnt(0)
	v_add3_u32 v233, s18, v144, v145
	ds_write_b128 v233, v[104:107] offset:0
	v_add_u32_e32 v233, s18, v236
	ds_write_b128 v233, v[108:111] offset:0
	v_add3_u32 v233, s18, v127, v126
	ds_write_b128 v233, v[112:115] offset:13312
	s_waitcnt lgkmcnt(9)
	v_mfma_f32_32x32x16_bf16 v[48:63], v[120:123], v[92:95], v[48:63]
	v_exp_f32_e32 v224, v72
	v_exp_f32_e32 v225, v73
	v_cvt_pk_bf16_f32 v200, v220, v221
	s_waitcnt lgkmcnt(4)
	v_mfma_f32_32x32x16_bf16 v[48:63], v[148:151], v[96:99], v[48:63]
	v_exp_f32_e32 v226, v74
	v_exp_f32_e32 v227, v75
	v_cvt_pk_bf16_f32 v201, v222, v223
	s_waitcnt lgkmcnt(3)
	v_mfma_f32_32x32x16_bf16 v[48:63], v[152:155], v[100:103], v[48:63]
	v_exp_f32_e32 v228, v76
	v_exp_f32_e32 v229, v77
	v_cvt_pk_bf16_f32 v208, v224, v225
	v_mfma_f32_32x32x16_bf16 v[32:47], v[190:193], v[212:215], v[32:47]
	v_exp_f32_e32 v230, v78
	ds_read_b128 v[190:193], v232 offset:13344
	v_exp_f32_e32 v231, v79
	v_cvt_pk_bf16_f32 v209, v226, v227
	v_mfma_f32_32x32x16_bf16 v[16:31], v[194:197], v[212:215], v[16:31]
	v_cvt_pk_bf16_f32 v210, v228, v229
	ds_read_b128 v[194:197], v232 offset:17952
	s_nop 0
	v_cvt_pk_bf16_f32 v211, v230, v231
	v_cmp_lt_f32_e32 vcc, 0x46800000, v234
	s_add_i32 s7, s7, 0x5800
	s_cmp_eq_u32 s7, 0x1b800
	s_cselect_b32 s7, 0, s7
	s_add_i32 s8, s8, 0x5800
	s_cmp_eq_u32 s8, 0x1b800
	s_cselect_b32 s8, 0, s8
	s_add_i32 s18, s18, 0x5800
	s_cmp_eq_u32 s18, 0x1b800
	s_cselect_b32 s18, 0, s18
	s_add_i32 s6, s6, 1
	s_cmp_eq_u32 s6, s5
	s_cbranch_scc1 .Lml_exit
	s_cbranch_vccnz .Lml_rare_l
	s_branch .Lml_top
; template <int D1, int D2, int DV>
; DI void attn_core(f32x16 (&o)[DV / 32], float& l_out, LAS unsigned char* lds, const bf16_t* q1, const bf16_t* q2,
;                   const bf16_t* k1, long ldk1, const bf16_t* k2, long ldk2, const bf16_t* vt, long ldv, int ntiles) {
;     ...
;         float ta = fmaxf(fmaxf(p[0][0], p[0][1]), p[1][0]), tb = fmaxf(fmaxf(p[0][2], p[0][3]), p[1][1]);
;         ta = fmaxf(fmaxf(ta, p[1][2]), p[1][3]);
; #pragma unroll
;         for (int i = 4; i < 16; i += 4) { ta = fmaxf(fmaxf(ta, p[0][i]), p[0][i + 1]); tb = fmaxf(fmaxf(tb, p[0][i + 2]), p[0][i + 3]); ta = fmaxf(fmaxf(ta, p[1][i]), p[1][i + 1]); tb = fmaxf(fmaxf(tb, p[1][i + 2]), p[1][i + 3]); }
;         float tm = fmaxf(ta, tb);
;         if (__any(t == 0 || tm > 8.0f)) {
;             tm = fmaxf(tm, __shfl_xor(tm, 32));
;             const float dl = (t == 0 || tm > 0.f) ? tm : 0.f; mrun += dl;
;             const float alpha = __builtin_amdgcn_exp2f(-dl); lrun *= alpha;
; #pragma unroll
;             for (int i = 0; i < 16; ++i) { p[0][i] -= dl; p[1][i] -= dl; negm[i] = -mrun; }
; #pragma unroll
;             for (int b = 0; b < DV / 32; ++b)
; #pragma unroll
;                 for (int i = 0; i < 16; ++i) o[b][i] *= alpha;
;         }
.Lml_rare_l:
	s_nop 15
	v_log_f32_e32 v234, v234
	s_nop 0
	v_add_f32_e32 v234, 0xc0a00000, v234
	s_nop 0
	ds_bpermute_b32 v116, v237, v234
	s_waitcnt lgkmcnt(0)
	v_max3_f32 v117, v234, v116, 0
	v_exp_f32_e64 v118, -v117
	v_add_f32_e32 v142, v142, v117
	v_xor_b32_e32 v0, 0x80000000, v142
	v_mov_b32_e32 v1, v0
	v_mov_b32_e32 v2, v0
	v_mov_b32_e32 v3, v0
	v_mov_b32_e32 v4, v0
	v_mov_b32_e32 v5, v0
	v_mov_b32_e32 v6, v0
	v_mov_b32_e32 v7, v0
	v_mov_b32_e32 v8, v0
	v_mov_b32_e32 v9, v0
	v_mov_b32_e32 v10, v0
	v_mov_b32_e32 v11, v0
	v_mov_b32_e32 v12, v0
	v_mov_b32_e32 v13, v0
	v_mov_b32_e32 v14, v0
	v_mov_b32_e32 v15, v0
	v_sub_f32_e32 v64, v64, v117
	v_sub_f32_e32 v65, v65, v117
	v_sub_f32_e32 v66, v66, v117
	v_sub_f32_e32 v67, v67, v117
	v_sub_f32_e32 v68, v68, v117
	v_sub_f32_e32 v69, v69, v117
	v_sub_f32_e32 v70, v70, v117
	v_sub_f32_e32 v71, v71, v117
	v_sub_f32_e32 v72, v72, v117
	v_sub_f32_e32 v73, v73, v117
	v_sub_f32_e32 v74, v74, v117
	v_sub_f32_e32 v75, v75, v117
	v_sub_f32_e32 v76, v76, v117
	v_sub_f32_e32 v77, v77, v117
	v_sub_f32_e32 v78, v78, v117
	v_sub_f32_e32 v79, v79, v117
	v_sub_f32_e32 v48, v48, v117
	v_sub_f32_e32 v49, v49, v117
	v_sub_f32_e32 v50, v50, v117
	v_sub_f32_e32 v51, v51, v117
	v_sub_f32_e32 v52, v52, v117
	v_sub_f32_e32 v53, v53, v117
	v_sub_f32_e32 v54, v54, v117
	v_sub_f32_e32 v55, v55, v117
	v_sub_f32_e32 v56, v56, v117
	v_sub_f32_e32 v57, v57, v117
	v_sub_f32_e32 v58, v58, v117
	v_sub_f32_e32 v59, v59, v117
	v_sub_f32_e32 v60, v60, v117
	v_sub_f32_e32 v61, v61, v117
	v_sub_f32_e32 v62, v62, v117
	v_sub_f32_e32 v63, v63, v117
	v_mul_f32_e32 v32, v32, v118
	v_mul_f32_e32 v33, v33, v118
	v_mul_f32_e32 v34, v34, v118
	v_mul_f32_e32 v35, v35, v118
	v_mul_f32_e32 v36, v36, v118
	v_mul_f32_e32 v37, v37, v118
	v_mul_f32_e32 v38, v38, v118
	v_mul_f32_e32 v39, v39, v118
	v_mul_f32_e32 v40, v40, v118
	v_mul_f32_e32 v41, v41, v118
	v_mul_f32_e32 v42, v42, v118
	v_mul_f32_e32 v43, v43, v118
	v_mul_f32_e32 v44, v44, v118
	v_mul_f32_e32 v45, v45, v118
	v_mul_f32_e32 v46, v46, v118
	v_mul_f32_e32 v47, v47, v118
	v_mul_f32_e32 v16, v16, v118
	v_mul_f32_e32 v17, v17, v118
	v_mul_f32_e32 v18, v18, v118
	v_mul_f32_e32 v19, v19, v118
	v_mul_f32_e32 v20, v20, v118
	v_mul_f32_e32 v21, v21, v118
	v_mul_f32_e32 v22, v22, v118
	v_mul_f32_e32 v23, v23, v118
	v_mul_f32_e32 v24, v24, v118
	v_mul_f32_e32 v25, v25, v118
	v_mul_f32_e32 v26, v26, v118
	v_mul_f32_e32 v27, v27, v118
	v_mul_f32_e32 v28, v28, v118
	v_mul_f32_e32 v29, v29, v118
	v_mul_f32_e32 v30, v30, v118
	v_mul_f32_e32 v31, v31, v118
	v_mul_f32_e32 v147, v147, v118
	v_exp_f32_e32 v216, v64
	v_exp_f32_e32 v217, v65
	v_exp_f32_e32 v218, v66
	v_exp_f32_e32 v219, v67
	v_exp_f32_e32 v220, v68
	v_exp_f32_e32 v221, v69
	v_exp_f32_e32 v222, v70
	v_exp_f32_e32 v223, v71
	v_exp_f32_e32 v224, v72
	v_exp_f32_e32 v225, v73
	v_exp_f32_e32 v226, v74
	v_exp_f32_e32 v227, v75
	v_exp_f32_e32 v228, v76
	v_exp_f32_e32 v229, v77
	v_exp_f32_e32 v230, v78
	v_exp_f32_e32 v231, v79
	s_nop 0
	v_cvt_pk_bf16_f32 v198, v216, v217
	v_cvt_pk_bf16_f32 v199, v218, v219
	v_cvt_pk_bf16_f32 v200, v220, v221
	v_cvt_pk_bf16_f32 v201, v222, v223
	v_cvt_pk_bf16_f32 v208, v224, v225
	v_cvt_pk_bf16_f32 v209, v226, v227
	v_cvt_pk_bf16_f32 v210, v228, v229
	v_cvt_pk_bf16_f32 v211, v230, v231
	s_nop 1
	s_branch .Lml_top
